# cooperative NSA selected branch: both cross-quad max steps via v_permlane16_swap / v_permlane32_swap, no ds_bpermute
# baseline (speedup 1.0000x reference)
; DI bf16_t f2bf(float f) { unsigned u = __float_as_uint(f); u += 0x7fffu + ((u >> 16) & 1u); return (bf16_t)(u >> 16); }
; DI float fexp(float x) { return __builtin_amdgcn_exp2f(x * 1.4426950408889634f); }
; #define MFMA16(a, b, c) __builtin_amdgcn_mfma_f32_16x16x32_bf16((a), (b), (c), 0, 0, 0)
; DI void sel_compute(const SelRegs& rg, const bf16x8 (&qf)[2], int kb0, bool colsel, int stk, int quad, float& m, float& lsum, f32x4 (&Os)[4]) {
;   f32x4 sa = {0.f, 0.f, 0.f, 0.f}, sb = {0.f, 0.f, 0.f, 0.f};
; #pragma unroll
;   for (int ks = 0; ks < 2; ++ks) { sa = MFMA16(__builtin_bit_cast(bf16x8, rg.ka[ks]), qf[ks], sa); sb = MFMA16(__builtin_bit_cast(bf16x8, rg.kb[ks]), qf[ks], sb); }
;   float mx = m;
; #pragma unroll
;   for (int i = 0; i < 4; ++i) { const int ka = kb0 + 8 * quad + i;
;     const float va = (colsel && ka <= stk) ? sa[i] * 0.125f : -1e30f, vb = (colsel && ka + 4 <= stk) ? sb[i] * 0.125f : -1e30f;
;     sa[i] = va; sb[i] = vb; mx = fmaxf(mx, fmaxf(va, vb)); }
;   mx = fmaxf(mx, __shfl_xor(mx, 16)); mx = fmaxf(mx, __shfl_xor(mx, 32));
;   const float corr = fexp(m - mx); m = mx; float ps = 0.f;
; #pragma unroll
;   for (int i = 0; i < 4; ++i) { const float pa = sa[i] > -1e29f ? fexp(sa[i] - mx) : 0.f, pb = sb[i] > -1e29f ? fexp(sb[i] - mx) : 0.f; sa[i] = pa; sb[i] = pb; ps += pa + pb; }
;   lsum = lsum * corr + ps;
;   bf16x8 pf;
; #pragma unroll
;   for (int i = 0; i < 4; ++i) { pf[i] = (short)f2bf(sa[i]); pf[4 + i] = (short)f2bf(sb[i]); }
; #pragma unroll
;   for (int dt = 0; dt < 4; ++dt) { Os[dt][0] *= corr; Os[dt][1] *= corr; Os[dt][2] *= corr; Os[dt][3] *= corr; Os[dt] = MFMA16(__builtin_bit_cast(bf16x8, rg.v[dt]), pf, Os[dt]); }
; }
.Lsc_noload:
	s_and_b32 s1, s5, 63
	v_readlane_b32 s0, v88, s1
	v_readlane_b32 s2, v89, s1
	s_cmp_lt_u32 s5, 64
	s_cselect_b32 s0, s0, s2
	s_lshr_b32 s0, s0, s4
	s_and_b32 s9, s0, 15
	s_cmp_eq_u32 s9, 0
	s_cbranch_scc1 .Lsc_skip
	v_add_u32_e32 v97, s7, v95
	v_add_u32_e32 v98, s7, v96
	ds_read_b128 v[40:43], v97 offset:20480
	ds_read_b128 v[44:47], v97 offset:21056
	ds_read_b128 v[48:51], v97 offset:20544
	ds_read_b128 v[52:55], v97 offset:21120
	ds_read_b128 v[56:59], v98 offset:29696
	ds_read_b128 v[60:63], v98 offset:32000
	ds_read_b128 v[64:67], v98 offset:34304
	ds_read_b128 v[68:71], v98 offset:36608
	s_lshl_b32 s12, s5, 6
	s_waitcnt lgkmcnt(4)
	v_mfma_f32_16x16x32_bf16 v[150:153], v[40:43], v[4:7], 0
	v_mfma_f32_16x16x32_bf16 v[154:157], v[44:47], v[4:7], 0
	v_mfma_f32_16x16x32_bf16 v[150:153], v[48:51], v[8:11], v[150:153]
	v_mfma_f32_16x16x32_bf16 v[154:157], v[52:55], v[8:11], v[154:157]
	v_and_b32_e32 v134, s9, v238
	v_cmp_ne_u32_e32 vcc, 0, v134
	v_subrev_u32_e32 v129, s12, v236
	s_nop 1
	v_cndmask_b32_e32 v134, -1, v129, vcc
	v_cmp_le_i32_e64 s[40:41], 0, v134
	v_cmp_le_i32_e64 s[42:43], 1, v134
	v_cmp_le_i32_e64 s[44:45], 2, v134
	v_cmp_le_i32_e64 s[46:47], 3, v134
	v_cndmask_b32_e64 v158, v240, 0, s[40:41]
	v_cndmask_b32_e64 v159, v240, 0, s[42:43]
	v_cndmask_b32_e64 v160, v240, 0, s[44:45]
	v_cndmask_b32_e64 v161, v240, 0, s[46:47]
	v_cmp_le_i32_e64 s[40:41], 4, v134
	v_cmp_le_i32_e64 s[42:43], 5, v134
	v_cmp_le_i32_e64 s[44:45], 6, v134
	v_cmp_le_i32_e64 s[46:47], 7, v134
	v_cndmask_b32_e64 v162, v240, 0, s[40:41]
	v_cndmask_b32_e64 v163, v240, 0, s[42:43]
	v_cndmask_b32_e64 v164, v240, 0, s[44:45]
	v_cndmask_b32_e64 v165, v240, 0, s[46:47]
	v_fma_f32 v150, v150, s6, v158
	v_fma_f32 v151, v151, s6, v159
	v_fma_f32 v152, v152, s6, v160
	v_fma_f32 v153, v153, s6, v161
	v_fma_f32 v154, v154, s6, v162
	v_fma_f32 v155, v155, s6, v163
	v_fma_f32 v156, v156, s6, v164
	v_fma_f32 v157, v157, s6, v165
	v_max3_f32 v128, v150, v151, v152
	v_max3_f32 v129, v153, v154, v155
	v_max3_f32 v133, v156, v157, v132
	v_max3_f32 v128, v128, v129, v133
	v_mov_b32_e32 v129, v128
	v_mov_b32_e32 v133, v128
	s_nop 1
	v_permlane16_swap_b32_e32 v129, v133
	v_max_f32_e32 v128, v129, v133
	v_mov_b32_e32 v129, v128
	v_mov_b32_e32 v133, v128
	s_nop 1
	v_permlane32_swap_b32_e32 v129, v133
	v_max_f32_e32 v128, v129, v133
	v_sub_f32_e32 v130, v132, v128
	v_exp_f32_e32 v130, v130
	v_mov_b32_e32 v132, v128
	v_sub_f32_e32 v150, v150, v128
	v_sub_f32_e32 v151, v151, v128
	v_sub_f32_e32 v152, v152, v128
	v_sub_f32_e32 v153, v153, v128
	v_sub_f32_e32 v154, v154, v128
	v_sub_f32_e32 v155, v155, v128
	v_sub_f32_e32 v156, v156, v128
	v_sub_f32_e32 v157, v157, v128
	v_exp_f32_e32 v150, v150
	v_exp_f32_e32 v151, v151
	v_exp_f32_e32 v152, v152
	v_exp_f32_e32 v153, v153
	v_exp_f32_e32 v154, v154
	v_exp_f32_e32 v155, v155
	v_exp_f32_e32 v156, v156
	v_exp_f32_e32 v157, v157
	v_pk_mul_f32 v[36:37], v[36:37], v[130:131] op_sel_hi:[1,0]
	v_pk_mul_f32 v[38:39], v[38:39], v[130:131] op_sel_hi:[1,0]
	v_pk_mul_f32 v[32:33], v[32:33], v[130:131] op_sel_hi:[1,0]
	v_pk_mul_f32 v[34:35], v[34:35], v[130:131] op_sel_hi:[1,0]
	v_pk_mul_f32 v[28:29], v[28:29], v[130:131] op_sel_hi:[1,0]
	v_pk_mul_f32 v[30:31], v[30:31], v[130:131] op_sel_hi:[1,0]
	v_pk_mul_f32 v[24:25], v[24:25], v[130:131] op_sel_hi:[1,0]
	v_pk_mul_f32 v[26:27], v[26:27], v[130:131] op_sel_hi:[1,0]
	v_add_f32_e32 v129, v150, v151
	v_add_f32_e32 v133, v152, v153
	v_add_f32_e32 v129, v129, v154
	v_add_f32_e32 v133, v133, v155
	v_add_f32_e32 v129, v129, v156
	v_add_f32_e32 v133, v133, v157
	v_add_f32_e32 v129, v129, v133
	v_fma_f32 v131, v131, v130, v129
	v_cvt_pk_bf16_f32 v166, v150, v151
	v_cvt_pk_bf16_f32 v167, v152, v153
	v_cvt_pk_bf16_f32 v168, v154, v155
	v_cvt_pk_bf16_f32 v169, v156, v157
	s_nop 1
	v_mfma_f32_16x16x32_bf16 v[36:39], v[56:59], v[166:169], v[36:39]
	v_mfma_f32_16x16x32_bf16 v[32:35], v[60:63], v[166:169], v[32:35]
	v_mfma_f32_16x16x32_bf16 v[28:31], v[64:67], v[166:169], v[28:31]
	v_mfma_f32_16x16x32_bf16 v[24:27], v[68:71], v[166:169], v[24:27]
	ds_read_b128 v[40:43], v97 offset:25088
	ds_read_b128 v[44:47], v97 offset:25664
	ds_read_b128 v[48:51], v97 offset:25152
	ds_read_b128 v[52:55], v97 offset:25728
	ds_read_b128 v[56:59], v98 offset:29760
	ds_read_b128 v[60:63], v98 offset:32064
	ds_read_b128 v[64:67], v98 offset:34368
	ds_read_b128 v[68:71], v98 offset:36672
	s_lshl_b32 s12, s5, 6
	s_add_i32 s12, s12, 32
	s_waitcnt lgkmcnt(4)
; DI bf16_t f2bf(float f) { unsigned u = __float_as_uint(f); u += 0x7fffu + ((u >> 16) & 1u); return (bf16_t)(u >> 16); }
; DI float fexp(float x) { return __builtin_amdgcn_exp2f(x * 1.4426950408889634f); }
; #define MFMA16(a, b, c) __builtin_amdgcn_mfma_f32_16x16x32_bf16((a), (b), (c), 0, 0, 0)
; DI void sel_compute(const SelRegs& rg, const bf16x8 (&qf)[2], int kb0, bool colsel, int stk, int quad, float& m, float& lsum, f32x4 (&Os)[4]) {
;   f32x4 sa = {0.f, 0.f, 0.f, 0.f}, sb = {0.f, 0.f, 0.f, 0.f};
; #pragma unroll
;   for (int ks = 0; ks < 2; ++ks) { sa = MFMA16(__builtin_bit_cast(bf16x8, rg.ka[ks]), qf[ks], sa); sb = MFMA16(__builtin_bit_cast(bf16x8, rg.kb[ks]), qf[ks], sb); }
;   float mx = m;
; #pragma unroll
;   for (int i = 0; i < 4; ++i) { const int ka = kb0 + 8 * quad + i;
;     const float va = (colsel && ka <= stk) ? sa[i] * 0.125f : -1e30f, vb = (colsel && ka + 4 <= stk) ? sb[i] * 0.125f : -1e30f;
;     sa[i] = va; sb[i] = vb; mx = fmaxf(mx, fmaxf(va, vb)); }
;   mx = fmaxf(mx, __shfl_xor(mx, 16)); mx = fmaxf(mx, __shfl_xor(mx, 32));
;   const float corr = fexp(m - mx); m = mx; float ps = 0.f;
; #pragma unroll
;   for (int i = 0; i < 4; ++i) { const float pa = sa[i] > -1e29f ? fexp(sa[i] - mx) : 0.f, pb = sb[i] > -1e29f ? fexp(sb[i] - mx) : 0.f; sa[i] = pa; sb[i] = pb; ps += pa + pb; }
;   lsum = lsum * corr + ps;
;   bf16x8 pf;
; #pragma unroll
;   for (int i = 0; i < 4; ++i) { pf[i] = (short)f2bf(sa[i]); pf[4 + i] = (short)f2bf(sb[i]); }
; #pragma unroll
;   for (int dt = 0; dt < 4; ++dt) { Os[dt][0] *= corr; Os[dt][1] *= corr; Os[dt][2] *= corr; Os[dt][3] *= corr; Os[dt] = MFMA16(__builtin_bit_cast(bf16x8, rg.v[dt]), pf, Os[dt]); }
; }
	v_mfma_f32_16x16x32_bf16 v[150:153], v[40:43], v[4:7], 0
	v_mfma_f32_16x16x32_bf16 v[154:157], v[44:47], v[4:7], 0
	v_mfma_f32_16x16x32_bf16 v[150:153], v[48:51], v[8:11], v[150:153]
	v_mfma_f32_16x16x32_bf16 v[154:157], v[52:55], v[8:11], v[154:157]
	v_and_b32_e32 v134, s9, v238
	v_cmp_ne_u32_e32 vcc, 0, v134
	v_subrev_u32_e32 v129, s12, v236
	s_nop 1
	v_cndmask_b32_e32 v134, -1, v129, vcc
	v_cmp_le_i32_e64 s[40:41], 0, v134
	v_cmp_le_i32_e64 s[42:43], 1, v134
	v_cmp_le_i32_e64 s[44:45], 2, v134
	v_cmp_le_i32_e64 s[46:47], 3, v134
	v_cndmask_b32_e64 v158, v240, 0, s[40:41]
	v_cndmask_b32_e64 v159, v240, 0, s[42:43]
	v_cndmask_b32_e64 v160, v240, 0, s[44:45]
	v_cndmask_b32_e64 v161, v240, 0, s[46:47]
	v_cmp_le_i32_e64 s[40:41], 4, v134
	v_cmp_le_i32_e64 s[42:43], 5, v134
	v_cmp_le_i32_e64 s[44:45], 6, v134
	v_cmp_le_i32_e64 s[46:47], 7, v134
	v_cndmask_b32_e64 v162, v240, 0, s[40:41]
	v_cndmask_b32_e64 v163, v240, 0, s[42:43]
	v_cndmask_b32_e64 v164, v240, 0, s[44:45]
	v_cndmask_b32_e64 v165, v240, 0, s[46:47]
	v_fma_f32 v150, v150, s6, v158
	v_fma_f32 v151, v151, s6, v159
	v_fma_f32 v152, v152, s6, v160
	v_fma_f32 v153, v153, s6, v161
	v_fma_f32 v154, v154, s6, v162
	v_fma_f32 v155, v155, s6, v163
	v_fma_f32 v156, v156, s6, v164
	v_fma_f32 v157, v157, s6, v165
	v_max3_f32 v128, v150, v151, v152
	v_max3_f32 v129, v153, v154, v155
	v_max3_f32 v133, v156, v157, v132
	v_max3_f32 v128, v128, v129, v133
	v_mov_b32_e32 v129, v128
	v_mov_b32_e32 v133, v128
	s_nop 1
	v_permlane16_swap_b32_e32 v129, v133
	v_max_f32_e32 v128, v129, v133
	v_mov_b32_e32 v129, v128
	v_mov_b32_e32 v133, v128
	s_nop 1
	v_permlane32_swap_b32_e32 v129, v133
	v_max_f32_e32 v128, v129, v133
	v_sub_f32_e32 v130, v132, v128
	v_exp_f32_e32 v130, v130
	v_mov_b32_e32 v132, v128
	v_sub_f32_e32 v150, v150, v128
	v_sub_f32_e32 v151, v151, v128
	v_sub_f32_e32 v152, v152, v128
	v_sub_f32_e32 v153, v153, v128
	v_sub_f32_e32 v154, v154, v128
	v_sub_f32_e32 v155, v155, v128
	v_sub_f32_e32 v156, v156, v128
	v_sub_f32_e32 v157, v157, v128
	v_exp_f32_e32 v150, v150
	v_exp_f32_e32 v151, v151
	v_exp_f32_e32 v152, v152
	v_exp_f32_e32 v153, v153
	v_exp_f32_e32 v154, v154
	v_exp_f32_e32 v155, v155
	v_exp_f32_e32 v156, v156
	v_exp_f32_e32 v157, v157
	v_pk_mul_f32 v[36:37], v[36:37], v[130:131] op_sel_hi:[1,0]
	v_pk_mul_f32 v[38:39], v[38:39], v[130:131] op_sel_hi:[1,0]
	v_pk_mul_f32 v[32:33], v[32:33], v[130:131] op_sel_hi:[1,0]
	v_pk_mul_f32 v[34:35], v[34:35], v[130:131] op_sel_hi:[1,0]
	v_pk_mul_f32 v[28:29], v[28:29], v[130:131] op_sel_hi:[1,0]
	v_pk_mul_f32 v[30:31], v[30:31], v[130:131] op_sel_hi:[1,0]
	v_pk_mul_f32 v[24:25], v[24:25], v[130:131] op_sel_hi:[1,0]
	v_pk_mul_f32 v[26:27], v[26:27], v[130:131] op_sel_hi:[1,0]
	v_add_f32_e32 v129, v150, v151
	v_add_f32_e32 v133, v152, v153
	v_add_f32_e32 v129, v129, v154
	v_add_f32_e32 v133, v133, v155
	v_add_f32_e32 v129, v129, v156
	v_add_f32_e32 v133, v133, v157
	v_add_f32_e32 v129, v129, v133
	v_fma_f32 v131, v131, v130, v129
	v_cvt_pk_bf16_f32 v166, v150, v151
	v_cvt_pk_bf16_f32 v167, v152, v153
	v_cvt_pk_bf16_f32 v168, v154, v155
	v_cvt_pk_bf16_f32 v169, v156, v157
	s_nop 1
	v_mfma_f32_16x16x32_bf16 v[36:39], v[56:59], v[166:169], v[36:39]
	v_mfma_f32_16x16x32_bf16 v[32:35], v[60:63], v[166:169], v[32:35]
	v_mfma_f32_16x16x32_bf16 v[28:31], v[64:67], v[166:169], v[28:31]
	v_mfma_f32_16x16x32_bf16 v[24:27], v[68:71], v[166:169], v[24:27]
